# chunk-item loads hoisted (one round trip) + attention QK reads 6-deep + 4-chain row sum
# speedup vs baseline: 1.0042x; 1.0042x over previous
; DI float bf_lo(unsigned u) { return __uint_as_float(u << 16); }
; DI float bf_hi(unsigned u) { return __uint_as_float(u & 0xffff0000u); }
; DI void chunk_item(const Params& p, int l, int item, char* lds) {
;     ...
;   {
;     const int t = t0 + ptok; const size_t row = (size_t)(row0 + ptok);
; #pragma unroll
;     for (int g = 0; g < 5; ++g) {
;       const int zc = (g < 3 ? g * 512 + h * 64 : 1536 + (g - 3) * 64) + pcs;
;       const u32x4 cu = *(const u32x4*)(p.z + row * NZ + zc);
;       float cur[8], prv[8];
; #pragma unroll
;       for (int e = 0; e < 4; ++e) { cur[2 * e] = bf_lo(cu[e]); cur[2 * e + 1] = bf_hi(cu[e]); }
;       if (t > 0) {
;         const u32x4 pu = *(const u32x4*)(p.z + (row - 1) * NZ + zc);
; #pragma unroll
;         for (int e = 0; e < 4; ++e) { prv[2 * e] = bf_lo(pu[e]); prv[2 * e + 1] = bf_hi(pu[e]); }
;       } else if (isp) {
; #pragma unroll
;         for (int e = 0; e < 8; ++e) prv[e] = 0.f;
;       } else {
;         const float* sp = p.sshift + (size_t)(l * 8 + b) * SHC + zc;
; #pragma unroll
;         for (int e = 0; e < 8; ++e) prv[e] = sp[e];
;       }
;       float zs[8];
; #pragma unroll
;       for (int e = 0; e < 8; ++e) zs[e] = cur[e] + (prv[e] - cur[e]) * mu[zc + e];
;       if (g < 3) {
;         float* d = (g == 0 ? s_r : g == 1 ? s_kf : s_v) + ptok * 64 + pcs;
;         *(f32x4*)d = (f32x4){zs[0], zs[1], zs[2], zs[3]}; *(f32x4*)(d + 4) = (f32x4){zs[4], zs[5], zs[6], zs[7]};
.LBB0_258:
	v_mov_b32_e32 v81, v212
	s_lshl_b32 s0, s22, 5
	s_and_b32 s0, s0, 0xfe0
	s_lshl_b32 s1, s22, 2
	s_lshr_b32 s20, s22, 1
	v_ashrrev_i32_e32 v42, 3, v81
	v_lshlrev_b32_e32 v0, 3, v81
	s_and_b32 s1, s1, 0xfffff000
	s_and_b32 s23, s20, 0x1c0
	v_and_b32_e32 v43, 56, v0
	v_add_u32_e32 v10, s0, v42
	v_add_u32_e32 v0, s1, v10
	v_or_b32_e32 v20, s23, v43
	v_mov_b64_e32 v[2:3], s[10:11]
	v_mad_i64_i32 v[6:7], s[0:1], v0, s94, v[2:3]
	v_lshlrev_b32_e32 v0, 1, v20
	v_lshl_add_u64 v[8:9], v[6:7], 0, v[0:1]
	global_load_dwordx4 v[2:5], v[8:9], off
	v_readfirstlane_b32 s20, v81
	v_cmp_lt_i32_e64 s[0:1], 0, v10
	global_load_dwordx4 v[50:53], v[8:9], off offset:1024
	global_load_dwordx4 v[54:57], v[8:9], off offset:2048
	v_lshlrev_b32_e32 v34, 1, v43
	v_mov_b32_e32 v35, 0
	v_lshl_add_u64 v[34:35], v[6:7], 0, v[34:35]
	global_load_dwordx4 v[58:61], v[34:35], off offset:3072
	global_load_dwordx4 v[62:65], v[34:35], off offset:3200
	s_and_saveexec_b64 s[24:25], s[0:1]
	v_add_co_u32_e32 v36, vcc, 0xffffd000, v8
	s_nop 1
	v_addc_co_u32_e32 v37, vcc, -1, v9, vcc
	global_load_dwordx4 v[66:69], v[36:37], off offset:-256
	global_load_dwordx4 v[70:73], v[36:37], off offset:768
	global_load_dwordx4 v[74:77], v[36:37], off offset:1792
	v_add_co_u32_e32 v38, vcc, 0xffffd000, v34
	s_nop 1
	v_addc_co_u32_e32 v39, vcc, -1, v35, vcc
	global_load_dwordx4 v[114:117], v[38:39], off offset:2816
	global_load_dwordx4 v[118:121], v[38:39], off offset:2944
	s_or_b64 exec, exec, s[24:25]
	v_mov_b32_e32 v10, 0
	v_mov_b32_e32 v12, 0
	v_mov_b32_e32 v13, 0
	v_mov_b32_e32 v14, 0
	v_mov_b32_e32 v15, 0
	v_mov_b32_e32 v16, 0
	v_mov_b32_e32 v17, 0
	v_mov_b32_e32 v18, 0
	v_mov_b32_e32 v19, 0
	s_and_saveexec_b64 s[24:25], s[0:1]
	s_cbranch_execz .LBB0_260
	s_waitcnt vmcnt(0)
	v_lshlrev_b32_e32 v16, 16, v66
	v_and_b32_e32 v17, 0xffff0000, v66
	v_lshlrev_b32_e32 v18, 16, v67
	v_and_b32_e32 v19, 0xffff0000, v67
	v_lshlrev_b32_e32 v12, 16, v68
	v_and_b32_e32 v13, 0xffff0000, v68
	v_lshlrev_b32_e32 v14, 16, v69
	v_and_b32_e32 v15, 0xffff0000, v69
.LBB0_260:
	s_or_b64 exec, exec, s[24:25]
	v_lshlrev_b32_e32 v0, 2, v20
	s_waitcnt vmcnt(0)
	v_lshlrev_b32_e32 v26, 16, v2
	v_and_b32_e32 v27, 0xffff0000, v2
	v_lshlrev_b32_e32 v28, 16, v3
	v_and_b32_e32 v29, 0xffff0000, v3
	v_lshlrev_b32_e32 v30, 16, v4
	v_and_b32_e32 v31, 0xffff0000, v4
	v_lshlrev_b32_e32 v32, 16, v5
	v_and_b32_e32 v33, 0xffff0000, v5
	global_load_dwordx4 v[2:5], v0, s[2:3] offset:16
	global_load_dwordx4 v[22:25], v0, s[2:3]
	v_lshlrev_b32_e32 v44, 8, v42
	v_pk_add_f32 v[16:17], v[16:17], v[26:27] neg_lo:[0,1] neg_hi:[0,1]
	v_pk_add_f32 v[18:19], v[18:19], v[28:29] neg_lo:[0,1] neg_hi:[0,1]
	v_pk_add_f32 v[12:13], v[12:13], v[30:31] neg_lo:[0,1] neg_hi:[0,1]
	v_pk_add_f32 v[14:15], v[14:15], v[32:33] neg_lo:[0,1] neg_hi:[0,1]
	v_lshl_or_b32 v45, v43, 2, v44
	v_mov_b32_e32 v11, 0
	s_waitcnt vmcnt(1)
	v_pk_fma_f32 v[2:3], v[12:13], v[2:3], v[30:31]
	s_waitcnt vmcnt(0)
	v_pk_fma_f32 v[16:17], v[16:17], v[22:23], v[26:27]
	v_pk_fma_f32 v[18:19], v[18:19], v[24:25], v[28:29]
	v_pk_fma_f32 v[4:5], v[14:15], v[4:5], v[32:33]
	ds_write_b128 v45, v[16:19]
	ds_write_b128 v45, v[2:5] offset:16
	v_mov_b32_e32 v12, 0
	v_mov_b32_e32 v13, 0
	v_mov_b32_e32 v14, 0
	v_mov_b32_e32 v15, 0
	v_mov_b32_e32 v16, 0
	v_mov_b32_e32 v17, 0
	s_and_saveexec_b64 s[24:25], s[0:1]
	s_cbranch_execz .LBB0_262
	s_waitcnt vmcnt(0)
	v_lshlrev_b32_e32 v14, 16, v70
	v_and_b32_e32 v15, 0xffff0000, v70
	v_lshlrev_b32_e32 v16, 16, v71
	v_and_b32_e32 v17, 0xffff0000, v71
	v_lshlrev_b32_e32 v10, 16, v72
	v_and_b32_e32 v11, 0xffff0000, v72
	v_lshlrev_b32_e32 v12, 16, v73
	v_and_b32_e32 v13, 0xffff0000, v73
.LBB0_262:
	s_or_b64 exec, exec, s[24:25]
	v_lshl_add_u64 v[18:19], s[2:3], 0, v[0:1]
	s_waitcnt vmcnt(0)
	v_lshlrev_b32_e32 v26, 16, v50
	v_and_b32_e32 v27, 0xffff0000, v50
	v_lshlrev_b32_e32 v28, 16, v51
	v_and_b32_e32 v29, 0xffff0000, v51
	v_lshlrev_b32_e32 v30, 16, v52
	v_and_b32_e32 v31, 0xffff0000, v52
	v_lshlrev_b32_e32 v32, 16, v53
	v_and_b32_e32 v33, 0xffff0000, v53
	global_load_dwordx4 v[2:5], v[18:19], off offset:2064
	global_load_dwordx4 v[22:25], v[18:19], off offset:2048
	v_pk_add_f32 v[14:15], v[14:15], v[26:27] neg_lo:[0,1] neg_hi:[0,1]
	v_pk_add_f32 v[16:17], v[16:17], v[28:29] neg_lo:[0,1] neg_hi:[0,1]
	v_pk_add_f32 v[10:11], v[10:11], v[30:31] neg_lo:[0,1] neg_hi:[0,1]
	v_pk_add_f32 v[12:13], v[12:13], v[32:33] neg_lo:[0,1] neg_hi:[0,1]
	s_waitcnt vmcnt(1)
	v_pk_fma_f32 v[2:3], v[10:11], v[2:3], v[30:31]
	s_waitcnt vmcnt(0)
	v_pk_fma_f32 v[14:15], v[14:15], v[22:23], v[26:27]
	v_pk_fma_f32 v[16:17], v[16:17], v[24:25], v[28:29]
	v_pk_fma_f32 v[4:5], v[12:13], v[4:5], v[32:33]
	ds_write_b128 v45, v[14:17] offset:8192
	ds_write_b128 v45, v[2:5] offset:8208
	v_or_b32_e32 v17, 0x400, v20
	v_mov_b32_e32 v16, 0
	v_mov_b32_e32 v8, 0
	v_mov_b32_e32 v9, 0
	v_mov_b32_e32 v10, 0
	v_mov_b32_e32 v11, 0
	v_mov_b32_e32 v12, 0
	v_mov_b32_e32 v13, 0
	v_mov_b32_e32 v14, 0
	v_mov_b32_e32 v15, 0
	s_and_saveexec_b64 s[24:25], s[0:1]
	s_cbranch_execz .LBB0_264
	s_waitcnt vmcnt(0)
	v_lshlrev_b32_e32 v12, 16, v74
	v_and_b32_e32 v13, 0xffff0000, v74
	v_lshlrev_b32_e32 v14, 16, v75
	v_and_b32_e32 v15, 0xffff0000, v75
	v_lshlrev_b32_e32 v8, 16, v76
	v_and_b32_e32 v9, 0xffff0000, v76
	v_lshlrev_b32_e32 v10, 16, v77
	v_and_b32_e32 v11, 0xffff0000, v77
; DI unsigned pk2(float a, float b) { f32x2 v = {a, b}; bfv2 r = __builtin_convertvector(v, bfv2); return __builtin_bit_cast(unsigned, r); }
; DI float bf_lo(unsigned u) { return __uint_as_float(u << 16); }
; DI float bf_hi(unsigned u) { return __uint_as_float(u & 0xffff0000u); }
; DI void chunk_item(const Params& p, int l, int item, char* lds) {
;     ...
;     for (int g = 0; g < 5; ++g) {
;       const int zc = (g < 3 ? g * 512 + h * 64 : 1536 + (g - 3) * 64) + pcs;
;       const u32x4 cu = *(const u32x4*)(p.z + row * NZ + zc);
;       float cur[8], prv[8];
; #pragma unroll
;       for (int e = 0; e < 4; ++e) { cur[2 * e] = bf_lo(cu[e]); cur[2 * e + 1] = bf_hi(cu[e]); }
;       if (t > 0) {
;         const u32x4 pu = *(const u32x4*)(p.z + (row - 1) * NZ + zc);
; #pragma unroll
;         for (int e = 0; e < 4; ++e) { prv[2 * e] = bf_lo(pu[e]); prv[2 * e + 1] = bf_hi(pu[e]); }
;       } else if (isp) {
; #pragma unroll
;         for (int e = 0; e < 8; ++e) prv[e] = 0.f;
;       } else {
;         const float* sp = p.sshift + (size_t)(l * 8 + b) * SHC + zc;
; #pragma unroll
;         for (int e = 0; e < 8; ++e) prv[e] = sp[e];
;       }
;       float zs[8];
; #pragma unroll
;       for (int e = 0; e < 8; ++e) zs[e] = cur[e] + (prv[e] - cur[e]) * mu[zc + e];
;       if (g < 3) {
;         float* d = (g == 0 ? s_r : g == 1 ? s_kf : s_v) + ptok * 64 + pcs;
;         *(f32x4*)d = (f32x4){zs[0], zs[1], zs[2], zs[3]}; *(f32x4*)(d + 4) = (f32x4){zs[4], zs[5], zs[6], zs[7]};
;       } else {
;         if (g == 3) {
; #pragma unroll
;           for (int e = 0; e < 8; ++e) { const float ex = __expf(2.f * zs[e]); zs[e] = 1.f - 2.f * __builtin_amdgcn_rcpf(ex + 1.f); }
;         }
;         u32x4 o; o[0] = pk2(zs[0], zs[1]); o[1] = pk2(zs[2], zs[3]); o[2] = pk2(zs[4], zs[5]); o[3] = pk2(zs[6], zs[7]);
;         *(u32x4*)((g == 3 ? s_wd : s_ad) + ptok * 72 + pcs) = o;
.LBB0_264:
	s_or_b64 exec, exec, s[24:25]
	v_lshlrev_b32_e32 v0, 2, v17
	s_waitcnt vmcnt(0)
	v_lshlrev_b32_e32 v22, 16, v54
	v_and_b32_e32 v23, 0xffff0000, v54
	v_lshlrev_b32_e32 v24, 16, v55
	v_and_b32_e32 v25, 0xffff0000, v55
	v_lshlrev_b32_e32 v26, 16, v56
	v_and_b32_e32 v27, 0xffff0000, v56
	v_lshlrev_b32_e32 v28, 16, v57
	v_and_b32_e32 v29, 0xffff0000, v57
	global_load_dwordx4 v[2:5], v0, s[2:3] offset:16
	global_load_dwordx4 v[18:21], v0, s[2:3]
	v_pk_add_f32 v[12:13], v[12:13], v[22:23] neg_lo:[0,1] neg_hi:[0,1]
	v_pk_add_f32 v[14:15], v[14:15], v[24:25] neg_lo:[0,1] neg_hi:[0,1]
	v_pk_add_f32 v[8:9], v[8:9], v[26:27] neg_lo:[0,1] neg_hi:[0,1]
	v_pk_add_f32 v[10:11], v[10:11], v[28:29] neg_lo:[0,1] neg_hi:[0,1]
	v_lshlrev_b32_e32 v0, 1, v43
	v_mov_b32_e32 v17, 0
	s_waitcnt vmcnt(1)
	v_pk_fma_f32 v[2:3], v[8:9], v[2:3], v[26:27]
	s_waitcnt vmcnt(0)
	v_pk_fma_f32 v[12:13], v[12:13], v[18:19], v[22:23]
	v_pk_fma_f32 v[14:15], v[14:15], v[20:21], v[24:25]
	v_pk_fma_f32 v[4:5], v[10:11], v[4:5], v[28:29]
	ds_write_b128 v45, v[12:15] offset:16384
	ds_write_b128 v45, v[2:5] offset:16400
	v_lshl_add_u64 v[8:9], v[6:7], 0, v[0:1]
	v_or_b32_e32 v10, 0x600, v43
	v_mov_b32_e32 v11, 0
	v_mov_b32_e32 v12, 0
	v_mov_b32_e32 v13, 0
	v_mov_b32_e32 v14, 0
	v_mov_b32_e32 v15, 0
	v_mov_b32_e32 v18, 0
	s_and_saveexec_b64 s[24:25], s[0:1]
	s_cbranch_execz .LBB0_266
	s_waitcnt vmcnt(0)
	v_lshlrev_b32_e32 v16, 16, v114
	v_and_b32_e32 v11, 0xffff0000, v114
	v_lshlrev_b32_e32 v12, 16, v115
	v_and_b32_e32 v13, 0xffff0000, v115
	v_lshlrev_b32_e32 v14, 16, v116
	v_and_b32_e32 v15, 0xffff0000, v116
	v_lshlrev_b32_e32 v17, 16, v117
	v_and_b32_e32 v18, 0xffff0000, v117
.LBB0_266:
	s_or_b64 exec, exec, s[24:25]
	v_lshlrev_b32_e32 v10, 2, v10
	s_waitcnt vmcnt(0)
	v_lshlrev_b32_e32 v19, 16, v58
	v_and_b32_e32 v24, 0xffff0000, v58
	v_lshlrev_b32_e32 v25, 16, v59
	v_and_b32_e32 v26, 0xffff0000, v59
	v_lshlrev_b32_e32 v27, 16, v60
	v_and_b32_e32 v28, 0xffff0000, v60
	v_lshlrev_b32_e32 v29, 16, v61
	v_and_b32_e32 v30, 0xffff0000, v61
	global_load_dwordx4 v[2:5], v10, s[2:3] offset:16
	global_load_dwordx4 v[20:23], v10, s[2:3]
	v_sub_f32_e32 v10, v11, v24
	v_sub_f32_e32 v16, v16, v19
	s_movk_i32 s21, 0xff90
	v_mul_lo_u32 v46, v42, s21
	s_waitcnt vmcnt(0)
	v_fmac_f32_e32 v24, v10, v21
	v_sub_f32_e32 v10, v12, v25
	v_fmac_f32_e32 v25, v10, v22
	v_sub_f32_e32 v10, v13, v26
	v_fmac_f32_e32 v26, v10, v23
	v_sub_f32_e32 v10, v14, v27
	v_fmac_f32_e32 v27, v10, v2
	v_sub_f32_e32 v2, v15, v28
	v_fmac_f32_e32 v28, v2, v3
	v_sub_f32_e32 v2, v17, v29
	v_fmac_f32_e32 v29, v2, v4
	v_sub_f32_e32 v2, v18, v30
	v_fmac_f32_e32 v19, v16, v20
	v_fmac_f32_e32 v30, v2, v5
	v_add_f32_e32 v2, v19, v19
	v_add_f32_e32 v3, v24, v24
	v_add_f32_e32 v4, v25, v25
	v_add_f32_e32 v5, v26, v26
	v_add_f32_e32 v10, v27, v27
	v_add_f32_e32 v11, v28, v28
	v_add_f32_e32 v12, v29, v29
	v_add_f32_e32 v13, v30, v30
	v_mul_f32_e32 v2, 0x3fb8aa3b, v2
	v_mul_f32_e32 v3, 0x3fb8aa3b, v3
	v_mul_f32_e32 v4, 0x3fb8aa3b, v4
	v_mul_f32_e32 v5, 0x3fb8aa3b, v5
	v_mul_f32_e32 v10, 0x3fb8aa3b, v10
	v_mul_f32_e32 v11, 0x3fb8aa3b, v11
	v_mul_f32_e32 v12, 0x3fb8aa3b, v12
	v_mul_f32_e32 v13, 0x3fb8aa3b, v13
	v_exp_f32_e32 v2, v2
	v_exp_f32_e32 v3, v3
	v_exp_f32_e32 v4, v4
	v_exp_f32_e32 v5, v5
	v_exp_f32_e32 v10, v10
	v_exp_f32_e32 v11, v11
	v_exp_f32_e32 v12, v12
	v_exp_f32_e32 v13, v13
	v_add_f32_e32 v2, 1.0, v2
	v_add_f32_e32 v3, 1.0, v3
	v_add_f32_e32 v4, 1.0, v4
	v_add_f32_e32 v5, 1.0, v5
	v_add_f32_e32 v10, 1.0, v10
	v_add_f32_e32 v11, 1.0, v11
	v_add_f32_e32 v12, 1.0, v12
	v_add_f32_e32 v13, 1.0, v13
	v_rcp_f32_e32 v2, v2
	v_rcp_f32_e32 v3, v3
	v_rcp_f32_e32 v4, v4
	v_rcp_f32_e32 v5, v5
	v_rcp_f32_e32 v10, v10
	v_rcp_f32_e32 v11, v11
	v_rcp_f32_e32 v12, v12
	v_rcp_f32_e32 v13, v13
	v_pk_fma_f32 v[2:3], v[2:3], 2.0, 1.0 op_sel_hi:[1,0,0] neg_lo:[1,0,0] neg_hi:[1,0,0]
	v_pk_fma_f32 v[4:5], v[4:5], 2.0, 1.0 op_sel_hi:[1,0,0] neg_lo:[1,0,0] neg_hi:[1,0,0]
	v_pk_fma_f32 v[10:11], v[10:11], 2.0, 1.0 op_sel_hi:[1,0,0] neg_lo:[1,0,0] neg_hi:[1,0,0]
	v_pk_fma_f32 v[12:13], v[12:13], 2.0, 1.0 op_sel_hi:[1,0,0] neg_lo:[1,0,0] neg_hi:[1,0,0]
	v_cvt_pk_bf16_f32 v2, v2, v3
	v_cvt_pk_bf16_f32 v3, v4, v5
	v_cvt_pk_bf16_f32 v4, v10, v11
	v_cvt_pk_bf16_f32 v5, v12, v13
	v_add3_u32 v16, v44, v46, v0
	ds_write_b128 v16, v[2:5] offset:49152
	v_or_b32_e32 v17, 0x640, v43
	v_mov_b32_e32 v8, 0
	v_mov_b32_e32 v9, 0
	v_mov_b32_e32 v10, 0
	v_mov_b32_e32 v11, 0
	v_mov_b32_e32 v12, 0
	v_mov_b32_e32 v13, 0
	v_mov_b32_e32 v14, 0
	v_mov_b32_e32 v15, 0
	s_and_saveexec_b64 s[24:25], s[0:1]
	s_cbranch_execz .LBB0_268
	s_waitcnt vmcnt(0)
	v_lshlrev_b32_e32 v14, 16, v118
	v_and_b32_e32 v15, 0xffff0000, v118
	v_lshlrev_b32_e32 v12, 16, v119
	v_and_b32_e32 v13, 0xffff0000, v119
	v_lshlrev_b32_e32 v10, 16, v120
	v_and_b32_e32 v11, 0xffff0000, v120
	v_lshlrev_b32_e32 v8, 16, v121
	v_and_b32_e32 v9, 0xffff0000, v121
; DI unsigned pk2(float a, float b) { f32x2 v = {a, b}; bfv2 r = __builtin_convertvector(v, bfv2); return __builtin_bit_cast(unsigned, r); }
; DI float sigmoidf_(float x) { return __builtin_amdgcn_rcpf(1.0f + __expf(-x)); }
; DI void chunk_item(const Params& p, int l, int item, char* lds) {
;     ...
;         u32x4 o; o[0] = pk2(zs[0], zs[1]); o[1] = pk2(zs[2], zs[3]); o[2] = pk2(zs[4], zs[5]); o[3] = pk2(zs[6], zs[7]);
;         *(u32x4*)((g == 3 ? s_wd : s_ad) + ptok * 72 + pcs) = o;
;       }
;     }
;   }
;   __syncthreads();
;   {
;     const bf16_t* At = (mat == 0 ? s_wd : s_ad);
;     bf16x8 af[2];
; #pragma unroll
;     for (int ks = 0; ks < 2; ++ks) af[ks] = *(const bf16x8*)(At + (tt * 16 + l15) * 72 + ks * 32 + quad * 8);
; #pragma unroll
;     for (int ct = 0; ct < 4; ++ct) {
;       f32x4 d = (f32x4){0.f, 0.f, 0.f, 0.f};
; #pragma unroll
;       for (int ks = 0; ks < 2; ++ks) {
;         const bf16x8 wfr = *(const bf16x8*)(wl + (size_t)(ct * 16 + l15) * 64 + ks * 32 + quad * 8);
;         d = __builtin_amdgcn_mfma_f32_16x16x32_bf16(wfr, af[ks], d, 0, 0, 0);
;       }
;       const int ch = ct * 16 + quad * 4; const int tok = tt * 16 + l15;
;       f32x4 o;
;       if (mat == 0) {
; #pragma unroll
;         for (int e = 0; e < 4; ++e) {
;           const float y = -(w0[ch + e] + d[e]);
;           const float sp = fmaxf(y, 0.f) + __logf(1.0f + __expf(-fabsf(y)));
;           o[e] = -__expf(-sp - 0.5f);
;         }
;         *(f32x4*)(s_w + tok * 64 + ch) = o;
;       } else {
; #pragma unroll
;         for (int e = 0; e < 4; ++e) o[e] = sigmoidf_(a0[ch + e] + d[e]);
;         *(f32x4*)(s_bb + tok * 64 + ch) = o;
;       }
;     }
.LBB0_268:
	s_or_b64 exec, exec, s[24:25]
	v_lshlrev_b32_e32 v17, 2, v17
	s_waitcnt vmcnt(0)
	v_lshlrev_b32_e32 v6, 16, v62
	v_and_b32_e32 v7, 0xffff0000, v62
	v_lshlrev_b32_e32 v22, 16, v63
	v_and_b32_e32 v23, 0xffff0000, v63
	v_lshlrev_b32_e32 v24, 16, v64
	v_and_b32_e32 v25, 0xffff0000, v64
	v_lshlrev_b32_e32 v26, 16, v65
	v_and_b32_e32 v27, 0xffff0000, v65
	global_load_dwordx4 v[2:5], v17, s[2:3] offset:16
	global_load_dwordx4 v[18:21], v17, s[2:3]
	s_cmpk_gt_u32 s20, 0x7f
	s_cselect_b64 s[30:31], -1, 0
	s_lshl_b32 s26, s23, 7
	s_bfe_u32 s21, s20, 0x10006
	s_lshl_b32 s23, s23, 2
	s_add_u32 s24, s76, s23
	s_addc_u32 s25, s77, 0
	s_cmpk_lt_u32 s20, 0x80
	s_cselect_b64 s[0:1], -1, 0
	v_pk_add_f32 v[10:11], v[10:11], v[24:25] neg_lo:[0,1] neg_hi:[0,1]
	s_and_b64 vcc, s[0:1], exec
	v_pk_add_f32 v[14:15], v[14:15], v[6:7] neg_lo:[0,1] neg_hi:[0,1]
	v_pk_add_f32 v[12:13], v[12:13], v[22:23] neg_lo:[0,1] neg_hi:[0,1]
	s_mov_b32 s27, 0xc000
	v_and_b32_e32 v112, 15, v81
	s_cselect_b32 s1, s5, s7
	s_cselect_b32 s0, s4, s6
	s_cselect_b32 s27, s27, 0xd200
	s_lshl_b32 s47, s21, 4
	v_bfe_u32 v47, v81, 4, 2
	s_add_u32 s0, s0, s26
	s_addc_u32 s1, s1, 0
	s_add_u32 s26, s78, s23
	v_lshlrev_b32_e32 v85, 2, v47
	v_lshlrev_b32_e32 v89, 2, v85
	s_waitcnt vmcnt(1)
	v_pk_fma_f32 v[10:11], v[10:11], v[2:3], v[24:25]
	v_pk_add_f32 v[2:3], v[8:9], v[26:27] neg_lo:[0,1] neg_hi:[0,1]
	s_waitcnt vmcnt(0)
	v_pk_fma_f32 v[6:7], v[14:15], v[18:19], v[6:7]
	v_pk_fma_f32 v[12:13], v[12:13], v[20:21], v[22:23]
	v_pk_fma_f32 v[8:9], v[2:3], v[4:5], v[26:27]
	v_cvt_pk_bf16_f32 v2, v6, v7
	v_cvt_pk_bf16_f32 v3, v12, v13
	v_cvt_pk_bf16_f32 v4, v10, v11
	v_cvt_pk_bf16_f32 v5, v8, v9
	v_or_b32_e32 v20, s47, v112
	ds_write_b128 v16, v[2:5] offset:53760
	v_mul_u32_u24_e32 v2, 0x90, v20
	v_lshlrev_b32_e32 v10, 4, v47
	v_mov_b32_e32 v11, v1
	v_add3_u32 v2, s27, v2, v10
	v_lshl_add_u64 v[10:11], s[0:1], 0, v[10:11]
	v_lshlrev_b32_e32 v12, 7, v112
	v_mov_b32_e32 v13, v1
	v_lshl_add_u64 v[18:19], v[10:11], 0, v[12:13]
	s_waitcnt lgkmcnt(0)
	s_barrier
	ds_read_b128 v[6:9], v2
	ds_read_b128 v[2:5], v2 offset:64
	global_load_dwordx4 v[10:13], v[18:19], off
	global_load_dwordx4 v[14:17], v[18:19], off offset:64
	s_addc_u32 s27, s79, 0
	s_cmpk_lt_u32 s20, 0x80
	s_cselect_b32 s68, s24, s26
	s_cselect_b32 s69, s25, s27
	s_mov_b64 s[70:71], 0x1000
	global_load_dwordx4 v[50:53], v[18:19], off offset:2048
	global_load_dwordx4 v[54:57], v[18:19], off offset:2112
	v_lshl_add_u64 v[38:39], v[18:19], 0, s[70:71]
	global_load_dwordx4 v[74:77], v89, s[68:69]
	global_load_dwordx4 v[58:61], v[38:39], off
	global_load_dwordx4 v[62:65], v[38:39], off offset:64
	global_load_dwordx4 v[114:117], v89, s[68:69] offset:64
	global_load_dwordx4 v[66:69], v[38:39], off offset:2048
	global_load_dwordx4 v[70:73], v[38:39], off offset:2112
	global_load_dwordx4 v[118:121], v89, s[68:69] offset:128
	global_load_dwordx4 v[122:125], v89, s[68:69] offset:192
	s_mov_b64 s[0:1], -1
	s_waitcnt vmcnt(1) lgkmcnt(1)
	v_mfma_f32_16x16x32_bf16 v[10:13], v[10:13], v[6:9], 0
	s_waitcnt vmcnt(0) lgkmcnt(0)
	v_mfma_f32_16x16x32_bf16 v[14:17], v[14:17], v[2:5], v[10:13]
	s_cbranch_vccnz .LBB0_270
	s_nop 4
	s_nop 0
	s_mov_b64 s[0:1], 0
	s_waitcnt vmcnt(0)
	v_add_f32_e32 v10, v14, v74
	v_add_f32_e32 v11, v15, v75
	v_add_f32_e32 v12, v16, v76
	v_add_f32_e32 v13, v17, v77
	v_mul_f32_e32 v10, 0xbfb8aa3b, v10
	v_mul_f32_e32 v11, 0xbfb8aa3b, v11
	v_mul_f32_e32 v12, 0xbfb8aa3b, v12
	v_mul_f32_e32 v13, 0xbfb8aa3b, v13
	v_exp_f32_e32 v10, v10
	v_exp_f32_e32 v11, v11
	v_exp_f32_e32 v12, v12
	v_exp_f32_e32 v13, v13
	v_add_f32_e32 v10, 1.0, v10
	v_add_f32_e32 v11, 1.0, v11
	v_add_f32_e32 v12, 1.0, v12
	v_add_f32_e32 v13, 1.0, v13
	v_rcp_f32_e32 v10, v10
	v_rcp_f32_e32 v11, v11
	v_rcp_f32_e32 v12, v12
	v_rcp_f32_e32 v13, v13
.LBB0_270:
	s_andn2_b64 vcc, exec, s[0:1]
	s_mov_b32 s0, 0xa000
	s_cbranch_vccnz .LBB0_272
	s_nop 1
	s_nop 0
	s_mov_b32 s36, 0xbfb8aa3b
	s_mov_b32 s37, 0x3f317217
	s_mov_b32 s38, 0x7f800000
	s_waitcnt vmcnt(0)
	v_add_f32_e32 v10, v14, v74
	v_max_f32_e64 v14, -v10, 0
	v_mul_f32_e64 v10, |v10|, s36
	v_exp_f32_e32 v10, v10
	v_add_f32_e32 v11, v15, v75
	v_add_f32_e32 v12, v16, v76
	v_add_f32_e32 v13, v17, v77
	v_add_f32_e32 v10, 1.0, v10
	v_cmp_gt_f32_e32 vcc, s34, v10
	s_nop 1
	v_cndmask_b32_e64 v21, 0, 32, vcc
	v_ldexp_f32 v10, v10, v21
	v_log_f32_e32 v10, v10
	s_nop 0
	v_mul_f32_e32 v21, 0x3f317217, v10
	v_fma_f32 v21, v10, s37, -v21
	v_fmac_f32_e32 v21, 0x3377d1cf, v10
	v_fmac_f32_e32 v21, 0x3f317217, v10
	v_cmp_lt_f32_e64 s[0:1], |v10|, s38
	s_nop 1
	v_cndmask_b32_e64 v10, v10, v21, s[0:1]
	v_cndmask_b32_e32 v21, 0, v230, vcc
	v_sub_f32_e32 v10, v10, v21
	v_add_f32_e32 v10, v14, v10
	v_max_f32_e64 v14, -v11, 0
	v_mul_f32_e64 v11, |v11|, s36
	v_exp_f32_e32 v11, v11
	v_sub_f32_e32 v10, -0.5, v10
	v_mul_f32_e32 v10, 0x3fb8aa3b, v10
	v_exp_f32_e32 v10, v10
	v_add_f32_e32 v11, 1.0, v11
	v_cmp_gt_f32_e32 vcc, s34, v11
	v_xor_b32_e32 v10, 0x80000000, v10
	s_nop 0
	v_cndmask_b32_e64 v15, 0, 32, vcc
	v_ldexp_f32 v11, v11, v15
	v_log_f32_e32 v11, v11
	s_nop 0
	v_mul_f32_e32 v15, 0x3f317217, v11
	v_fma_f32 v15, v11, s37, -v15
	v_fmac_f32_e32 v15, 0x3377d1cf, v11
	v_fmac_f32_e32 v15, 0x3f317217, v11
	v_cmp_lt_f32_e64 s[0:1], |v11|, s38
	s_nop 1
	v_cndmask_b32_e64 v11, v11, v15, s[0:1]
	v_cndmask_b32_e32 v15, 0, v230, vcc
	v_sub_f32_e32 v11, v11, v15
	v_add_f32_e32 v11, v14, v11
	v_max_f32_e64 v14, -v12, 0
	v_mul_f32_e64 v12, |v12|, s36
	v_exp_f32_e32 v12, v12
	v_sub_f32_e32 v11, -0.5, v11
	v_mul_f32_e32 v11, 0x3fb8aa3b, v11
	v_exp_f32_e32 v11, v11
	v_add_f32_e32 v12, 1.0, v12
	v_cmp_gt_f32_e32 vcc, s34, v12
	v_xor_b32_e32 v11, 0x80000000, v11
	s_nop 0
	v_cndmask_b32_e64 v15, 0, 32, vcc
	v_ldexp_f32 v12, v12, v15
	v_log_f32_e32 v12, v12
	s_nop 0
	v_mul_f32_e32 v15, 0x3f317217, v12
	v_fma_f32 v15, v12, s37, -v15
	v_fmac_f32_e32 v15, 0x3377d1cf, v12
	v_fmac_f32_e32 v15, 0x3f317217, v12
	v_cmp_lt_f32_e64 s[0:1], |v12|, s38
	s_nop 1
	v_cndmask_b32_e64 v12, v12, v15, s[0:1]
	v_cndmask_b32_e32 v15, 0, v230, vcc
	v_sub_f32_e32 v12, v12, v15
	v_add_f32_e32 v12, v14, v12
	v_max_f32_e64 v14, -v13, 0
	v_mul_f32_e64 v13, |v13|, s36
	v_exp_f32_e32 v13, v13
	v_sub_f32_e32 v12, -0.5, v12
	v_mul_f32_e32 v12, 0x3fb8aa3b, v12
	v_exp_f32_e32 v12, v12
	v_add_f32_e32 v13, 1.0, v13
	v_cmp_gt_f32_e32 vcc, s34, v13
	v_xor_b32_e32 v12, 0x80000000, v12
	s_nop 0
	v_cndmask_b32_e64 v15, 0, 32, vcc
	v_ldexp_f32 v13, v13, v15
	v_log_f32_e32 v13, v13
	s_nop 0
	v_mul_f32_e32 v15, 0x3f317217, v13
	v_fma_f32 v15, v13, s37, -v15
	v_fmac_f32_e32 v15, 0x3377d1cf, v13
	v_fmac_f32_e32 v15, 0x3f317217, v13
	v_cmp_lt_f32_e64 s[0:1], |v13|, s38
	s_nop 1
	v_cndmask_b32_e64 v13, v13, v15, s[0:1]
	v_cndmask_b32_e32 v15, 0, v230, vcc
	v_sub_f32_e32 v13, v13, v15
	v_add_f32_e32 v13, v14, v13
	v_sub_f32_e32 v13, -0.5, v13
	v_mul_f32_e32 v13, 0x3fb8aa3b, v13
	v_exp_f32_e32 v13, v13
	s_movk_i32 s0, 0x6000
	v_xor_b32_e32 v13, 0x80000000, v13
; DI float sigmoidf_(float x) { return __builtin_amdgcn_rcpf(1.0f + __expf(-x)); }
; DI void chunk_item(const Params& p, int l, int item, char* lds) {
;     ...
;     for (int ct = 0; ct < 4; ++ct) {
;       f32x4 d = (f32x4){0.f, 0.f, 0.f, 0.f};
; #pragma unroll
;       for (int ks = 0; ks < 2; ++ks) {
;         const bf16x8 wfr = *(const bf16x8*)(wl + (size_t)(ct * 16 + l15) * 64 + ks * 32 + quad * 8);
;         d = __builtin_amdgcn_mfma_f32_16x16x32_bf16(wfr, af[ks], d, 0, 0, 0);
;       }
;       const int ch = ct * 16 + quad * 4; const int tok = tt * 16 + l15;
;       f32x4 o;
;       if (mat == 0) {
; #pragma unroll
;         for (int e = 0; e < 4; ++e) {
;           const float y = -(w0[ch + e] + d[e]);
;           const float sp = fmaxf(y, 0.f) + __logf(1.0f + __expf(-fabsf(y)));
;           o[e] = -__expf(-sp - 0.5f);
;         }
;         *(f32x4*)(s_w + tok * 64 + ch) = o;
;       } else {
; #pragma unroll
;         for (int e = 0; e < 4; ++e) o[e] = sigmoidf_(a0[ch + e] + d[e]);
;         *(f32x4*)(s_bb + tok * 64 + ch) = o;
;       }
.LBB0_272:
	v_lshlrev_b32_e32 v20, 8, v20
	s_nop 2
	v_add3_u32 v14, s0, v20, v89
	ds_write_b128 v14, v[10:13]
	s_nop 0
	s_nop 0
	s_mov_b64 s[36:37], -1
	s_andn2_b64 vcc, exec, s[30:31]
	s_waitcnt vmcnt(1)
	v_mfma_f32_16x16x32_bf16 v[10:13], v[50:53], v[6:9], 0
	s_waitcnt vmcnt(0)
	v_mfma_f32_16x16x32_bf16 v[14:17], v[54:57], v[2:5], v[10:13]
	s_nop 5
	v_cndmask_b32_e64 v10, 0, 1, s[30:31]
	v_cmp_ne_u32_e64 s[0:1], 1, v10
	s_cbranch_vccnz .LBB0_274
	s_nop 0
	s_mov_b64 s[36:37], 0
	s_waitcnt vmcnt(0)
	v_add_f32_e32 v10, v14, v114
	v_add_f32_e32 v11, v15, v115
	v_add_f32_e32 v12, v16, v116
	v_add_f32_e32 v13, v17, v117
	v_mul_f32_e32 v10, 0xbfb8aa3b, v10
	v_mul_f32_e32 v11, 0xbfb8aa3b, v11
	v_mul_f32_e32 v12, 0xbfb8aa3b, v12
	v_mul_f32_e32 v13, 0xbfb8aa3b, v13
	v_exp_f32_e32 v10, v10
	v_exp_f32_e32 v11, v11
	v_exp_f32_e32 v12, v12
	v_exp_f32_e32 v13, v13
	v_add_f32_e32 v10, 1.0, v10
	v_add_f32_e32 v11, 1.0, v11
	v_add_f32_e32 v12, 1.0, v12
	v_add_f32_e32 v13, 1.0, v13
	v_rcp_f32_e32 v10, v10
	v_rcp_f32_e32 v11, v11
	v_rcp_f32_e32 v12, v12
	v_rcp_f32_e32 v13, v13
.LBB0_274:
	s_andn2_b64 vcc, exec, s[36:37]
	s_mov_b32 s30, 0xa000
	s_cbranch_vccnz .LBB0_276
	s_nop 0
	s_mov_b32 s30, 0xbfb8aa3b
	s_mov_b32 s31, 0x3f317217
	s_mov_b32 s38, 0x7f800000
	s_waitcnt vmcnt(0)
	v_add_f32_e32 v10, v14, v114
	v_max_f32_e64 v14, -v10, 0
	v_mul_f32_e64 v10, |v10|, s30
	v_exp_f32_e32 v10, v10
	v_add_f32_e32 v11, v15, v115
	v_add_f32_e32 v12, v16, v116
	v_add_f32_e32 v13, v17, v117
	v_add_f32_e32 v10, 1.0, v10
	v_cmp_gt_f32_e32 vcc, s34, v10
	s_nop 1
	v_cndmask_b32_e64 v21, 0, 32, vcc
	v_ldexp_f32 v10, v10, v21
	v_log_f32_e32 v10, v10
	s_nop 0
	v_mul_f32_e32 v21, 0x3f317217, v10
	v_fma_f32 v21, v10, s31, -v21
	v_fmac_f32_e32 v21, 0x3377d1cf, v10
	v_fmac_f32_e32 v21, 0x3f317217, v10
	v_cmp_lt_f32_e64 s[36:37], |v10|, s38
	s_nop 1
	v_cndmask_b32_e64 v10, v10, v21, s[36:37]
	v_cndmask_b32_e32 v21, 0, v230, vcc
	v_sub_f32_e32 v10, v10, v21
	v_add_f32_e32 v10, v14, v10
	v_max_f32_e64 v14, -v11, 0
	v_mul_f32_e64 v11, |v11|, s30
	v_exp_f32_e32 v11, v11
	v_sub_f32_e32 v10, -0.5, v10
	v_mul_f32_e32 v10, 0x3fb8aa3b, v10
	v_exp_f32_e32 v10, v10
	v_add_f32_e32 v11, 1.0, v11
	v_cmp_gt_f32_e32 vcc, s34, v11
	v_xor_b32_e32 v10, 0x80000000, v10
	s_nop 0
	v_cndmask_b32_e64 v15, 0, 32, vcc
	v_ldexp_f32 v11, v11, v15
	v_log_f32_e32 v11, v11
	s_nop 0
	v_mul_f32_e32 v15, 0x3f317217, v11
	v_fma_f32 v15, v11, s31, -v15
	v_fmac_f32_e32 v15, 0x3377d1cf, v11
	v_fmac_f32_e32 v15, 0x3f317217, v11
	v_cmp_lt_f32_e64 s[36:37], |v11|, s38
	s_nop 1
	v_cndmask_b32_e64 v11, v11, v15, s[36:37]
	v_cndmask_b32_e32 v15, 0, v230, vcc
	v_sub_f32_e32 v11, v11, v15
	v_add_f32_e32 v11, v14, v11
	v_max_f32_e64 v14, -v12, 0
	v_mul_f32_e64 v12, |v12|, s30
	v_exp_f32_e32 v12, v12
	v_sub_f32_e32 v11, -0.5, v11
	v_mul_f32_e32 v11, 0x3fb8aa3b, v11
	v_exp_f32_e32 v11, v11
	v_add_f32_e32 v12, 1.0, v12
	v_cmp_gt_f32_e32 vcc, s34, v12
	v_xor_b32_e32 v11, 0x80000000, v11
	s_nop 0
	v_cndmask_b32_e64 v15, 0, 32, vcc
	v_ldexp_f32 v12, v12, v15
	v_log_f32_e32 v12, v12
	s_nop 0
	v_mul_f32_e32 v15, 0x3f317217, v12
	v_fma_f32 v15, v12, s31, -v15
	v_fmac_f32_e32 v15, 0x3377d1cf, v12
	v_fmac_f32_e32 v15, 0x3f317217, v12
	v_cmp_lt_f32_e64 s[36:37], |v12|, s38
	s_nop 1
	v_cndmask_b32_e64 v12, v12, v15, s[36:37]
	v_cndmask_b32_e32 v15, 0, v230, vcc
	v_sub_f32_e32 v12, v12, v15
	v_add_f32_e32 v12, v14, v12
	v_max_f32_e64 v14, -v13, 0
	v_mul_f32_e64 v13, |v13|, s30
	v_exp_f32_e32 v13, v13
	v_sub_f32_e32 v12, -0.5, v12
	v_mul_f32_e32 v12, 0x3fb8aa3b, v12
	v_exp_f32_e32 v12, v12
	v_add_f32_e32 v13, 1.0, v13
	v_cmp_gt_f32_e32 vcc, s34, v13
	s_movk_i32 s30, 0x6000
	v_xor_b32_e32 v12, 0x80000000, v12
	v_cndmask_b32_e64 v15, 0, 32, vcc
	v_ldexp_f32 v13, v13, v15
	v_log_f32_e32 v13, v13
	s_nop 0
	v_mul_f32_e32 v15, 0x3f317217, v13
	v_fma_f32 v15, v13, s31, -v15
	v_fmac_f32_e32 v15, 0x3377d1cf, v13
	v_fmac_f32_e32 v15, 0x3f317217, v13
	v_cmp_lt_f32_e64 s[36:37], |v13|, s38
	s_nop 1
	v_cndmask_b32_e64 v13, v13, v15, s[36:37]
	v_cndmask_b32_e32 v15, 0, v230, vcc
	v_sub_f32_e32 v13, v13, v15
	v_add_f32_e32 v13, v14, v13
	v_sub_f32_e32 v13, -0.5, v13
	v_mul_f32_e32 v13, 0x3fb8aa3b, v13
	v_exp_f32_e32 v13, v13
	s_nop 0
	v_xor_b32_e32 v13, 0x80000000, v13
.LBB0_276:
	v_add3_u32 v14, s30, v20, v89
	ds_write_b128 v14, v[10:13] offset:64
	v_add_co_u32_e32 v14, vcc, 0x1000, v18
	s_mov_b64 s[30:31], -1
	s_nop 0
	v_addc_co_u32_e32 v15, vcc, 0, v19, vcc
	s_nop 0
	s_and_b64 vcc, exec, s[0:1]
	s_nop 0
	s_waitcnt vmcnt(1)
	v_mfma_f32_16x16x32_bf16 v[10:13], v[58:61], v[6:9], 0
	s_waitcnt vmcnt(0)
	v_mfma_f32_16x16x32_bf16 v[14:17], v[62:65], v[2:5], v[10:13]
	s_cbranch_vccnz .LBB0_278
	s_nop 4
	s_nop 0
	s_mov_b64 s[30:31], 0
	s_waitcnt vmcnt(0)
	v_add_f32_e32 v10, v14, v118
	v_add_f32_e32 v11, v15, v119
	v_add_f32_e32 v12, v16, v120
	v_add_f32_e32 v13, v17, v121
	v_mul_f32_e32 v10, 0xbfb8aa3b, v10
	v_mul_f32_e32 v11, 0xbfb8aa3b, v11
	v_mul_f32_e32 v12, 0xbfb8aa3b, v12
	v_mul_f32_e32 v13, 0xbfb8aa3b, v13
	v_exp_f32_e32 v10, v10
	v_exp_f32_e32 v11, v11
	v_exp_f32_e32 v12, v12
	v_exp_f32_e32 v13, v13
	v_add_f32_e32 v10, 1.0, v10
	v_add_f32_e32 v11, 1.0, v11
	v_add_f32_e32 v12, 1.0, v12
	v_add_f32_e32 v13, 1.0, v13
	v_rcp_f32_e32 v10, v10
	v_rcp_f32_e32 v11, v11
	v_rcp_f32_e32 v12, v12
	v_rcp_f32_e32 v13, v13
; DI void chunk_item(const Params& p, int l, int item, char* lds) {
;     ...
;       if (mat == 0) {
; #pragma unroll
;         for (int e = 0; e < 4; ++e) {
;           const float y = -(w0[ch + e] + d[e]);
;           const float sp = fmaxf(y, 0.f) + __logf(1.0f + __expf(-fabsf(y)));
;           o[e] = -__expf(-sp - 0.5f);
;         }
;         *(f32x4*)(s_w + tok * 64 + ch) = o;
.LBB0_278:
	s_andn2_b64 vcc, exec, s[30:31]
	s_mov_b32 s30, 0xa000
	s_cbranch_vccnz .LBB0_280
	s_nop 1
	s_nop 0
	s_mov_b32 s30, 0xbfb8aa3b
	s_mov_b32 s31, 0x3f317217
	s_mov_b32 s38, 0x7f800000
	s_waitcnt vmcnt(0)
	v_add_f32_e32 v10, v14, v118
	v_max_f32_e64 v14, -v10, 0
	v_mul_f32_e64 v10, |v10|, s30
	v_exp_f32_e32 v10, v10
	v_add_f32_e32 v11, v15, v119
	v_add_f32_e32 v12, v16, v120
	v_add_f32_e32 v13, v17, v121
	v_add_f32_e32 v10, 1.0, v10
	v_cmp_gt_f32_e32 vcc, s34, v10
	s_nop 1
	v_cndmask_b32_e64 v21, 0, 32, vcc
	v_ldexp_f32 v10, v10, v21
	v_log_f32_e32 v10, v10
	s_nop 0
	v_mul_f32_e32 v21, 0x3f317217, v10
	v_fma_f32 v21, v10, s31, -v21
	v_fmac_f32_e32 v21, 0x3377d1cf, v10
	v_fmac_f32_e32 v21, 0x3f317217, v10
	v_cmp_lt_f32_e64 s[36:37], |v10|, s38
	s_nop 1
	v_cndmask_b32_e64 v10, v10, v21, s[36:37]
	v_cndmask_b32_e32 v21, 0, v230, vcc
	v_sub_f32_e32 v10, v10, v21
	v_add_f32_e32 v10, v14, v10
	v_max_f32_e64 v14, -v11, 0
	v_mul_f32_e64 v11, |v11|, s30
	v_exp_f32_e32 v11, v11
	v_sub_f32_e32 v10, -0.5, v10
	v_mul_f32_e32 v10, 0x3fb8aa3b, v10
	v_exp_f32_e32 v10, v10
	v_add_f32_e32 v11, 1.0, v11
	v_cmp_gt_f32_e32 vcc, s34, v11
	v_xor_b32_e32 v10, 0x80000000, v10
	s_nop 0
	v_cndmask_b32_e64 v15, 0, 32, vcc
	v_ldexp_f32 v11, v11, v15
	v_log_f32_e32 v11, v11
	s_nop 0
	v_mul_f32_e32 v15, 0x3f317217, v11
	v_fma_f32 v15, v11, s31, -v15
	v_fmac_f32_e32 v15, 0x3377d1cf, v11
	v_fmac_f32_e32 v15, 0x3f317217, v11
	v_cmp_lt_f32_e64 s[36:37], |v11|, s38
	s_nop 1
	v_cndmask_b32_e64 v11, v11, v15, s[36:37]
	v_cndmask_b32_e32 v15, 0, v230, vcc
	v_sub_f32_e32 v11, v11, v15
	v_add_f32_e32 v11, v14, v11
	v_max_f32_e64 v14, -v12, 0
	v_mul_f32_e64 v12, |v12|, s30
	v_exp_f32_e32 v12, v12
	v_sub_f32_e32 v11, -0.5, v11
	v_mul_f32_e32 v11, 0x3fb8aa3b, v11
	v_exp_f32_e32 v11, v11
	v_add_f32_e32 v12, 1.0, v12
	v_cmp_gt_f32_e32 vcc, s34, v12
	v_xor_b32_e32 v11, 0x80000000, v11
	s_nop 0
	v_cndmask_b32_e64 v15, 0, 32, vcc
	v_ldexp_f32 v12, v12, v15
	v_log_f32_e32 v12, v12
	s_nop 0
	v_mul_f32_e32 v15, 0x3f317217, v12
	v_fma_f32 v15, v12, s31, -v15
	v_fmac_f32_e32 v15, 0x3377d1cf, v12
	v_fmac_f32_e32 v15, 0x3f317217, v12
	v_cmp_lt_f32_e64 s[36:37], |v12|, s38
	s_nop 1
	v_cndmask_b32_e64 v12, v12, v15, s[36:37]
	v_cndmask_b32_e32 v15, 0, v230, vcc
	v_sub_f32_e32 v12, v12, v15
	v_add_f32_e32 v12, v14, v12
	v_max_f32_e64 v14, -v13, 0
	v_mul_f32_e64 v13, |v13|, s30
	v_exp_f32_e32 v13, v13
	v_sub_f32_e32 v12, -0.5, v12
	v_mul_f32_e32 v12, 0x3fb8aa3b, v12
	v_exp_f32_e32 v12, v12
	v_add_f32_e32 v13, 1.0, v13
	v_cmp_gt_f32_e32 vcc, s34, v13
	s_movk_i32 s30, 0x6000
	v_xor_b32_e32 v12, 0x80000000, v12
	v_cndmask_b32_e64 v15, 0, 32, vcc
	v_ldexp_f32 v13, v13, v15
	v_log_f32_e32 v13, v13
	s_nop 0
	v_mul_f32_e32 v15, 0x3f317217, v13
	v_fma_f32 v15, v13, s31, -v15
	v_fmac_f32_e32 v15, 0x3377d1cf, v13
	v_fmac_f32_e32 v15, 0x3f317217, v13
	v_cmp_lt_f32_e64 s[36:37], |v13|, s38
	s_nop 1
	v_cndmask_b32_e64 v13, v13, v15, s[36:37]
	v_cndmask_b32_e32 v15, 0, v230, vcc
	v_sub_f32_e32 v13, v13, v15
	v_add_f32_e32 v13, v14, v13
	v_sub_f32_e32 v13, -0.5, v13
	v_mul_f32_e32 v13, 0x3fb8aa3b, v13
	v_exp_f32_e32 v13, v13
	s_nop 0
	v_xor_b32_e32 v13, 0x80000000, v13
; DI float sigmoidf_(float x) { return __builtin_amdgcn_rcpf(1.0f + __expf(-x)); }
; DI void chunk_item(const Params& p, int l, int item, char* lds) {
;     ...
;     for (int ct = 0; ct < 4; ++ct) {
;       f32x4 d = (f32x4){0.f, 0.f, 0.f, 0.f};
; #pragma unroll
;       for (int ks = 0; ks < 2; ++ks) {
;         const bf16x8 wfr = *(const bf16x8*)(wl + (size_t)(ct * 16 + l15) * 64 + ks * 32 + quad * 8);
;         d = __builtin_amdgcn_mfma_f32_16x16x32_bf16(wfr, af[ks], d, 0, 0, 0);
;       }
;       const int ch = ct * 16 + quad * 4; const int tok = tt * 16 + l15;
;       f32x4 o;
;       if (mat == 0) {
; #pragma unroll
;         for (int e = 0; e < 4; ++e) {
;           const float y = -(w0[ch + e] + d[e]);
;           const float sp = fmaxf(y, 0.f) + __logf(1.0f + __expf(-fabsf(y)));
;           o[e] = -__expf(-sp - 0.5f);
;         }
;         *(f32x4*)(s_w + tok * 64 + ch) = o;
;       } else {
; #pragma unroll
;         for (int e = 0; e < 4; ++e) o[e] = sigmoidf_(a0[ch + e] + d[e]);
;         *(f32x4*)(s_bb + tok * 64 + ch) = o;
;       }
.LBB0_280:
	s_nop 3
	v_add3_u32 v14, s30, v20, v89
	ds_write_b128 v14, v[10:13] offset:128
	v_add_co_u32_e32 v14, vcc, 0x1000, v18
	s_mov_b64 s[30:31], -1
	s_nop 0
	v_addc_co_u32_e32 v15, vcc, 0, v19, vcc
	s_nop 0
	s_and_b64 vcc, exec, s[0:1]
	s_waitcnt vmcnt(0)
	v_mfma_f32_16x16x32_bf16 v[6:9], v[66:69], v[6:9], 0
	s_nop 0
	s_waitcnt vmcnt(0)
	v_mfma_f32_16x16x32_bf16 v[6:9], v[70:73], v[2:5], v[6:9]
	s_cbranch_vccnz .LBB0_282
	s_nop 0
	s_mov_b64 s[30:31], 0
	s_waitcnt vmcnt(0)
	s_nop 3
	v_add_f32_e32 v2, v6, v122
	v_add_f32_e32 v3, v7, v123
	v_add_f32_e32 v4, v8, v124
	v_add_f32_e32 v5, v9, v125
	v_mul_f32_e32 v2, 0xbfb8aa3b, v2
	v_mul_f32_e32 v3, 0xbfb8aa3b, v3
	v_mul_f32_e32 v4, 0xbfb8aa3b, v4
	v_mul_f32_e32 v5, 0xbfb8aa3b, v5
	v_exp_f32_e32 v2, v2
	v_exp_f32_e32 v3, v3
	v_exp_f32_e32 v4, v4
	v_exp_f32_e32 v5, v5
	v_add_f32_e32 v2, 1.0, v2
	v_add_f32_e32 v3, 1.0, v3
	v_add_f32_e32 v4, 1.0, v4
	v_add_f32_e32 v5, 1.0, v5
	v_rcp_f32_e32 v2, v2
	v_rcp_f32_e32 v3, v3
	v_rcp_f32_e32 v4, v4
	v_rcp_f32_e32 v5, v5
.LBB0_282:
	s_andn2_b64 vcc, exec, s[30:31]
	s_mov_b32 s0, 0xa000
	s_cbranch_vccnz .LBB0_284
	s_nop 0
	s_mov_b32 s24, 0xbfb8aa3b
	s_mov_b32 s25, 0x3f317217
	s_mov_b32 s26, 0x7f800000
	s_waitcnt vmcnt(0)
	v_add_f32_e32 v2, v6, v122
	v_max_f32_e64 v6, -v2, 0
	v_mul_f32_e64 v2, |v2|, s24
	v_exp_f32_e32 v2, v2
	v_add_f32_e32 v3, v7, v123
	v_add_f32_e32 v4, v8, v124
	v_add_f32_e32 v5, v9, v125
	v_add_f32_e32 v2, 1.0, v2
	v_cmp_gt_f32_e32 vcc, s34, v2
	s_nop 1
	v_cndmask_b32_e64 v10, 0, 32, vcc
	v_ldexp_f32 v2, v2, v10
	v_log_f32_e32 v2, v2
	s_nop 0
	v_mul_f32_e32 v10, 0x3f317217, v2
	v_fma_f32 v10, v2, s25, -v10
	v_fmac_f32_e32 v10, 0x3377d1cf, v2
	v_fmac_f32_e32 v10, 0x3f317217, v2
	v_cmp_lt_f32_e64 s[0:1], |v2|, s26
	s_nop 1
	v_cndmask_b32_e64 v2, v2, v10, s[0:1]
	v_cndmask_b32_e32 v10, 0, v230, vcc
	v_sub_f32_e32 v2, v2, v10
	v_add_f32_e32 v2, v6, v2
	v_max_f32_e64 v6, -v3, 0
	v_mul_f32_e64 v3, |v3|, s24
	v_exp_f32_e32 v3, v3
	v_sub_f32_e32 v2, -0.5, v2
	v_mul_f32_e32 v2, 0x3fb8aa3b, v2
	v_exp_f32_e32 v2, v2
	v_add_f32_e32 v3, 1.0, v3
	v_cmp_gt_f32_e32 vcc, s34, v3
	v_xor_b32_e32 v2, 0x80000000, v2
	s_nop 0
	v_cndmask_b32_e64 v7, 0, 32, vcc
	v_ldexp_f32 v3, v3, v7
	v_log_f32_e32 v3, v3
	s_nop 0
	v_mul_f32_e32 v7, 0x3f317217, v3
	v_fma_f32 v7, v3, s25, -v7
	v_fmac_f32_e32 v7, 0x3377d1cf, v3
	v_fmac_f32_e32 v7, 0x3f317217, v3
	v_cmp_lt_f32_e64 s[0:1], |v3|, s26
	s_nop 1
	v_cndmask_b32_e64 v3, v3, v7, s[0:1]
	v_cndmask_b32_e32 v7, 0, v230, vcc
	v_sub_f32_e32 v3, v3, v7
	v_add_f32_e32 v3, v6, v3
	v_max_f32_e64 v6, -v4, 0
	v_mul_f32_e64 v4, |v4|, s24
	v_exp_f32_e32 v4, v4
	v_sub_f32_e32 v3, -0.5, v3
	v_mul_f32_e32 v3, 0x3fb8aa3b, v3
	v_exp_f32_e32 v3, v3
	v_add_f32_e32 v4, 1.0, v4
	v_cmp_gt_f32_e32 vcc, s34, v4
	v_xor_b32_e32 v3, 0x80000000, v3
	s_nop 0
	v_cndmask_b32_e64 v7, 0, 32, vcc
	v_ldexp_f32 v4, v4, v7
	v_log_f32_e32 v4, v4
	s_nop 0
	v_mul_f32_e32 v7, 0x3f317217, v4
	v_fma_f32 v7, v4, s25, -v7
	v_fmac_f32_e32 v7, 0x3377d1cf, v4
	v_fmac_f32_e32 v7, 0x3f317217, v4
	v_cmp_lt_f32_e64 s[0:1], |v4|, s26
	s_nop 1
	v_cndmask_b32_e64 v4, v4, v7, s[0:1]
	v_cndmask_b32_e32 v7, 0, v230, vcc
	v_sub_f32_e32 v4, v4, v7
	v_add_f32_e32 v4, v6, v4
	v_max_f32_e64 v6, -v5, 0
	v_mul_f32_e64 v5, |v5|, s24
	v_exp_f32_e32 v5, v5
	v_sub_f32_e32 v4, -0.5, v4
	v_mul_f32_e32 v4, 0x3fb8aa3b, v4
	v_exp_f32_e32 v4, v4
	v_add_f32_e32 v5, 1.0, v5
	v_cmp_gt_f32_e32 vcc, s34, v5
	v_xor_b32_e32 v4, 0x80000000, v4
	s_nop 0
	v_cndmask_b32_e64 v7, 0, 32, vcc
	v_ldexp_f32 v5, v5, v7
	v_log_f32_e32 v5, v5
	s_nop 0
	v_mul_f32_e32 v7, 0x3f317217, v5
	v_fma_f32 v7, v5, s25, -v7
	v_fmac_f32_e32 v7, 0x3377d1cf, v5
	v_fmac_f32_e32 v7, 0x3f317217, v5
	v_cmp_lt_f32_e64 s[0:1], |v5|, s26
	s_nop 1
	v_cndmask_b32_e64 v5, v5, v7, s[0:1]
	v_cndmask_b32_e32 v7, 0, v230, vcc
	v_sub_f32_e32 v5, v5, v7
	v_add_f32_e32 v5, v6, v5
	v_sub_f32_e32 v5, -0.5, v5
	v_mul_f32_e32 v5, 0x3fb8aa3b, v5
	v_exp_f32_e32 v5, v5
	s_movk_i32 s0, 0x6000
	v_xor_b32_e32 v5, 0x80000000, v5

; DI void attn_item(const Params& p, int l, int item, char* lds) {
;     ...
;     for (int kt = 0; kt < 2; ++kt) {
; #pragma unroll
;       for (int e = 0; e < 16; ++e) s[kt][e] = 0.f;
; #pragma unroll
;       for (int ks = 0; ks < 4; ++ks) {
;         const bf16x8 kf = *(const bf16x8*)(Ks + (m * 64 + kt * 32 + q) * ALD + ks * 16 + hh * 8);
;         s[kt] = __builtin_amdgcn_mfma_f32_32x32x16_bf16(kf, qf[ks], s[kt], 0, 0, 0);
;       }
;     }
;     float mx = -1e30f;
;     const float dbase = qposf - (float)(j * 64 + 4 * hh);
; #pragma unroll
;     for (int kt = 0; kt < 2; ++kt)
; #pragma unroll
;       for (int e = 0; e < 16; ++e) {
;         const float dd = dbase - (float)(kt * 32 + (e & 3) + 8 * (e >> 2));
;         const float v = s[kt][e] * c1 - sl2 * fabsf(dd);
;         s[kt][e] = v; mx = fmaxf(mx, v);
;       }
;     mx = fmaxf(mx, __shfl_xor(mx, 32));
;     const float mnew = fmaxf(mrun, mx);
;     const float alpha = __builtin_amdgcn_exp2f(mrun - mnew);
;     const bool resc = mnew > mrun;
;     mrun = mnew;
.LBB0_600:
	ds_read_b128 v[2:5], v202
	ds_read_b128 v[6:9], v202 offset:32
	ds_read_b128 v[10:13], v202 offset:64
	ds_read_b128 v[214:217], v202 offset:96
	ds_read_b128 v[222:225], v202 offset:4608
	ds_read_b128 v[226:229], v202 offset:4640
	v_cvt_f32_u32_e32 v0, v199
	s_mov_b32 s2, 0xf149f2ca
	v_sub_f32_e32 v0, v187, v0
	s_waitcnt lgkmcnt(5)
	v_mfma_f32_32x32x16_bf16 v[96:111], v[2:5], v[120:123], 0
	ds_read_b128 v[2:5], v202 offset:4672
	s_waitcnt lgkmcnt(5)
	v_mfma_f32_32x32x16_bf16 v[96:111], v[6:9], v[112:115], v[96:111]
	ds_read_b128 v[6:9], v202 offset:4704
	s_waitcnt lgkmcnt(5)
	v_mfma_f32_32x32x16_bf16 v[96:111], v[10:13], v[116:119], v[96:111]
	s_waitcnt lgkmcnt(4)
	v_mfma_f32_32x32x16_bf16 v[96:111], v[214:217], v[124:127], v[96:111]
	s_waitcnt lgkmcnt(3)
	v_mfma_f32_32x32x16_bf16 v[80:95], v[222:225], v[120:123], 0
	s_waitcnt lgkmcnt(2)
	v_mfma_f32_32x32x16_bf16 v[80:95], v[226:229], v[112:115], v[80:95]
	s_waitcnt lgkmcnt(1)
	v_mfma_f32_32x32x16_bf16 v[80:95], v[2:5], v[116:119], v[80:95]
	s_waitcnt lgkmcnt(0)
	v_mfma_f32_32x32x16_bf16 v[80:95], v[6:9], v[124:127], v[80:95]
	v_add_f32_e32 v11, 0xc2640000, v0
	v_add_f32_e32 v9, 0xc24c0000, v0
	v_add_f32_e32 v5, -2.0, v0
	v_mul_f32_e64 v2, v189, |v0|
	v_mul_f32_e64 v5, v189, |v5|
	v_fma_f32 v3, v96, s35, -v2
	v_fma_f32 v96, v98, s35, -v5
	v_add_f32_e32 v5, 0xc0400000, v0
	v_mul_f32_e64 v5, v189, |v5|
	v_fma_f32 v173, v99, s35, -v5
	v_add_f32_e32 v5, 0xc1000000, v0
	v_mul_f32_e64 v5, v189, |v5|
	v_fma_f32 v205, v100, s35, -v5
	v_add_f32_e32 v5, 0xc1100000, v0
	v_mul_f32_e64 v5, v189, |v5|
	v_fma_f32 v206, v101, s35, -v5
	v_add_f32_e32 v5, 0xc1200000, v0
	v_mul_f32_e64 v5, v189, |v5|
	v_fma_f32 v10, v102, s35, -v5
	v_add_f32_e32 v5, 0xc1300000, v0
	v_mul_f32_e64 v5, v189, |v5|
	v_fma_f32 v13, v103, s35, -v5
	v_add_f32_e32 v5, 0xc1800000, v0
	v_mul_f32_e64 v5, v189, |v5|
	v_fma_f32 v15, v104, s35, -v5
	v_add_f32_e32 v5, 0xc1880000, v0
	v_mul_f32_e64 v5, v189, |v5|
	v_fma_f32 v103, v105, s35, -v5
	v_add_f32_e32 v5, 0xc1900000, v0
	v_mul_f32_e64 v5, v189, |v5|
	v_fma_f32 v105, v106, s35, -v5
	v_add_f32_e32 v5, 0xc1980000, v0
	v_mul_f32_e64 v5, v189, |v5|
	v_fma_f32 v107, v107, s35, -v5
	v_add_f32_e32 v5, 0xc1c00000, v0
	v_mul_f32_e64 v5, v189, |v5|
	v_fma_f32 v102, v108, s35, -v5
	v_add_f32_e32 v5, 0xc1c80000, v0
	v_mul_f32_e64 v5, v189, |v5|
	v_fma_f32 v104, v109, s35, -v5
	v_add_f32_e32 v5, 0xc1d00000, v0
	v_mul_f32_e64 v5, v189, |v5|
	v_fma_f32 v106, v110, s35, -v5
	v_add_f32_e32 v5, 0xc1d80000, v0
	v_mul_f32_e64 v5, v189, |v5|
	v_fma_f32 v101, v111, s35, -v5
	v_add_f32_e32 v5, 0xc2000000, v0
	v_mul_f32_e64 v5, v189, |v5|
	v_add_f32_e32 v2, -1.0, v0
	v_fma_f32 v100, v80, s35, -v5
	v_add_f32_e32 v5, 0xc2040000, v0
	v_mul_f32_e64 v2, v189, |v2|
	v_mul_f32_e64 v5, v189, |v5|
	v_fma_f32 v4, v97, s35, -v2
	v_fma_f32 v97, v81, s35, -v5
	v_add_f32_e32 v5, 0xc2080000, v0
	v_mul_f32_e64 v5, v189, |v5|
	v_fma_f32 v98, v82, s35, -v5
	v_add_f32_e32 v5, 0xc20c0000, v0
	v_mul_f32_e64 v5, v189, |v5|
	v_fma_f32 v99, v83, s35, -v5
	v_add_f32_e32 v5, 0xc2200000, v0
	v_mul_f32_e64 v5, v189, |v5|
	v_fma_f32 v80, v84, s35, -v5
	v_add_f32_e32 v5, 0xc2240000, v0
	v_mul_f32_e64 v5, v189, |v5|
	v_max3_f32 v2, v3, s2, v4
	v_fma_f32 v81, v85, s35, -v5
	v_add_f32_e32 v5, 0xc2280000, v0
	v_max3_f32 v2, v2, v96, v173
	v_mul_f32_e64 v5, v189, |v5|
	v_max3_f32 v2, v2, v205, v206
	v_fma_f32 v82, v86, s35, -v5
	v_add_f32_e32 v5, 0xc22c0000, v0
	v_max3_f32 v2, v2, v10, v13
	v_and_b32_e32 v161, 0x7fffffff, v5
	v_mov_b32_e32 v188, v87
	v_add_f32_e32 v5, 0xc2400000, v0
	v_max3_f32 v2, v2, v15, v103
	v_pk_mul_f32 v[6:7], v[188:189], v[160:161]
	v_and_b32_e32 v161, 0x7fffffff, v5
	v_mov_b32_e32 v188, v88
	v_max3_f32 v2, v2, v105, v107
	v_sub_f32_e32 v8, v6, v7
	v_pk_mul_f32 v[6:7], v[188:189], v[160:161]
	v_add_f32_e32 v5, 0xc2440000, v0
	v_max3_f32 v2, v2, v102, v104
	v_sub_f32_e32 v6, v6, v7
	v_and_b32_e32 v161, 0x7fffffff, v5
	v_mov_b32_e32 v188, v89
	v_add_f32_e32 v7, 0xc2480000, v0
	v_max3_f32 v2, v2, v106, v101
	v_pk_mul_f32 v[84:85], v[188:189], v[160:161]
	v_and_b32_e32 v161, 0x7fffffff, v7
	v_mov_b32_e32 v188, v90
	v_max3_f32 v2, v2, v100, v97
	v_sub_f32_e32 v5, v84, v85
	v_pk_mul_f32 v[84:85], v[188:189], v[160:161]
	v_and_b32_e32 v161, 0x7fffffff, v9
	v_mov_b32_e32 v188, v91
	v_add_f32_e32 v9, 0xc2600000, v0
	v_max3_f32 v2, v2, v98, v99
	v_sub_f32_e32 v7, v84, v85
	v_pk_mul_f32 v[84:85], v[188:189], v[160:161]
	v_and_b32_e32 v161, 0x7fffffff, v9
	v_mov_b32_e32 v188, v92
	v_max3_f32 v2, v2, v80, v81
	v_sub_f32_e32 v12, v84, v85
	v_pk_mul_f32 v[84:85], v[188:189], v[160:161]
	v_and_b32_e32 v161, 0x7fffffff, v11
	v_mov_b32_e32 v188, v93
	v_add_f32_e32 v11, 0xc2680000, v0
	v_max3_f32 v2, v2, v82, v8
	v_sub_f32_e32 v9, v84, v85
	v_pk_mul_f32 v[84:85], v[188:189], v[160:161]
	v_and_b32_e32 v161, 0x7fffffff, v11
	v_mov_b32_e32 v188, v94
	v_add_f32_e32 v0, 0xc26c0000, v0
	v_max3_f32 v2, v2, v6, v5
	v_sub_f32_e32 v14, v84, v85
	v_pk_mul_f32 v[84:85], v[188:189], v[160:161]
	v_and_b32_e32 v161, 0x7fffffff, v0
	v_mov_b32_e32 v188, v95
	v_max3_f32 v2, v2, v7, v12
	v_sub_f32_e32 v83, v84, v85
	v_pk_mul_f32 v[84:85], v[188:189], v[160:161]
	v_max3_f32 v2, v2, v9, v14
	v_sub_f32_e32 v11, v84, v85
	v_max3_f32 v0, v2, v83, v11
	ds_bpermute_b32 v2, v200, v0
	s_waitcnt lgkmcnt(0)
	v_max3_f32 v2, v204, v0, v2
	v_sub_f32_e32 v0, v204, v2
	v_exp_f32_e32 v0, v0
	v_cmp_gt_f32_e32 vcc, v2, v204
	s_cbranch_vccz .LBB0_602
; DI void attn_item(const Params& p, int l, int item, char* lds) {
;     ...
;     if (__any(resc)) {
; #pragma unroll
;       for (int i = 0; i < 4; ++i)
; #pragma unroll
;         for (int e = 0; e < 16; ++e) O[i][e] *= alpha;
;     }
	v_pk_mul_f32 v[78:79], v[78:79], v[0:1] op_sel_hi:[1,0]
	v_pk_mul_f32 v[76:77], v[76:77], v[0:1] op_sel_hi:[1,0]
	v_pk_mul_f32 v[74:75], v[74:75], v[0:1] op_sel_hi:[1,0]
	v_pk_mul_f32 v[72:73], v[72:73], v[0:1] op_sel_hi:[1,0]
	v_pk_mul_f32 v[70:71], v[70:71], v[0:1] op_sel_hi:[1,0]
	v_pk_mul_f32 v[68:69], v[68:69], v[0:1] op_sel_hi:[1,0]
	v_pk_mul_f32 v[66:67], v[66:67], v[0:1] op_sel_hi:[1,0]
	v_pk_mul_f32 v[64:65], v[64:65], v[0:1] op_sel_hi:[1,0]
	v_pk_mul_f32 v[62:63], v[62:63], v[0:1] op_sel_hi:[1,0]
	v_pk_mul_f32 v[60:61], v[60:61], v[0:1] op_sel_hi:[1,0]
	v_pk_mul_f32 v[58:59], v[58:59], v[0:1] op_sel_hi:[1,0]
	v_pk_mul_f32 v[56:57], v[56:57], v[0:1] op_sel_hi:[1,0]
	v_pk_mul_f32 v[54:55], v[54:55], v[0:1] op_sel_hi:[1,0]
	v_pk_mul_f32 v[52:53], v[52:53], v[0:1] op_sel_hi:[1,0]
	v_pk_mul_f32 v[50:51], v[50:51], v[0:1] op_sel_hi:[1,0]
	v_pk_mul_f32 v[48:49], v[48:49], v[0:1] op_sel_hi:[1,0]
	v_pk_mul_f32 v[46:47], v[46:47], v[0:1] op_sel_hi:[1,0]
	v_pk_mul_f32 v[44:45], v[44:45], v[0:1] op_sel_hi:[1,0]
	v_pk_mul_f32 v[42:43], v[42:43], v[0:1] op_sel_hi:[1,0]
	v_pk_mul_f32 v[40:41], v[40:41], v[0:1] op_sel_hi:[1,0]
	v_pk_mul_f32 v[38:39], v[38:39], v[0:1] op_sel_hi:[1,0]
	v_pk_mul_f32 v[36:37], v[36:37], v[0:1] op_sel_hi:[1,0]
	v_pk_mul_f32 v[34:35], v[34:35], v[0:1] op_sel_hi:[1,0]
	v_pk_mul_f32 v[32:33], v[32:33], v[0:1] op_sel_hi:[1,0]
	v_pk_mul_f32 v[30:31], v[30:31], v[0:1] op_sel_hi:[1,0]
	v_pk_mul_f32 v[28:29], v[28:29], v[0:1] op_sel_hi:[1,0]
	v_pk_mul_f32 v[26:27], v[26:27], v[0:1] op_sel_hi:[1,0]
	v_pk_mul_f32 v[24:25], v[24:25], v[0:1] op_sel_hi:[1,0]
	v_pk_mul_f32 v[22:23], v[22:23], v[0:1] op_sel_hi:[1,0]
	v_pk_mul_f32 v[20:21], v[20:21], v[0:1] op_sel_hi:[1,0]
	v_pk_mul_f32 v[18:19], v[18:19], v[0:1] op_sel_hi:[1,0]
	v_pk_mul_f32 v[16:17], v[16:17], v[0:1] op_sel_hi:[1,0]

; DI void attn_item(const Params& p, int l, int item, char* lds) {
;     ...
;     float ps = 0.f;
; #pragma unroll
;     for (int kt = 0; kt < 2; ++kt)
; #pragma unroll
;       for (int e = 0; e < 16; ++e) { const float pe = __builtin_amdgcn_exp2f(s[kt][e] - mnew); s[kt][e] = pe; ps += pe; }
;     lrun = lrun * alpha + ps;
;     ...
;     __syncthreads();
;     if (j + 1 < nch) sstore();
;     __syncthreads();
;   }
.LBB0_604:
	v_add_f32_e32 v3, 0, v3
	v_add_f32_e32 v3, v4, v3
	v_add_f32_e32 v161, v84, v85
	v_add_f32_e32 v214, v86, v87
	v_add_f32_e32 v215, v10, v13
	v_add_f32_e32 v3, v15, v3
	v_add_f32_e32 v161, v88, v161
	v_add_f32_e32 v214, v89, v214
	v_add_f32_e32 v215, v90, v215
	v_add_f32_e32 v3, v91, v3
	v_add_f32_e32 v161, v92, v161
	v_add_f32_e32 v214, v93, v214
	v_add_f32_e32 v215, v94, v215
	v_add_f32_e32 v3, v95, v3
	v_add_f32_e32 v161, v96, v161
	v_add_f32_e32 v214, v97, v214
	v_add_f32_e32 v215, v98, v215
	v_add_f32_e32 v3, v80, v3
	v_add_f32_e32 v161, v81, v161
	v_add_f32_e32 v214, v82, v214
	v_add_f32_e32 v215, v8, v215
	v_add_f32_e32 v3, v6, v3
	v_add_f32_e32 v161, v5, v161
	v_add_f32_e32 v214, v7, v214
	v_add_f32_e32 v215, v12, v215
	v_add_f32_e32 v3, v9, v3
	v_add_f32_e32 v161, v14, v161
	v_add_f32_e32 v214, v83, v214
	v_add_f32_e32 v215, v11, v215
	s_add_u32 s36, s36, 0x80
	v_add_f32_e32 v3, v161, v3
	v_add_f32_e32 v214, v215, v214
	v_add_f32_e32 v3, v214, v3
	s_addc_u32 s37, s37, 0
	s_add_i32 s38, s38, 64
	s_add_i32 s92, s92, 64
	v_fmac_f32_e32 v3, v203, v0
	s_cmp_eq_u32 s44, s93
	v_add_u32_e32 v199, 64, v199
	s_waitcnt lgkmcnt(0)
	s_barrier
	s_cbranch_scc1 .LBB0_606
	v_mov_b32_e32 v203, v3
	v_mov_b32_e32 v204, v2
	s_mov_b32 s39, s93
	s_branch .LBB0_591
